# stack3 + gate/up SwiGLU epilogue: eight interleaved chains with the plain multiplies/adds as packed f32 pairs (v_pk_mul_f32 / v_pk_add_f32), same per-element operations
# baseline (speedup 1.0000x reference)
; __device__ __forceinline__ unsigned cvt_pk_bf16(float lo, float hi) { unsigned r; asm volatile("v_cvt_pk_bf16_f32 %0, %1, %2" : "=v"(r) : "v"(lo), "v"(hi)); return r; }
;     __device__ __forceinline__ void operator()(const f32x4 (&acc)[2][2][4][2], const Unit& u, int wr, int wc, int fr, int fq, const float (&rsv)[8]) const {
;         const int row0 = u.pm * BM + wr * 64 + fr, col0 = u.pn * HALF + wc * 32 + 8 * fq;
; #pragma unroll
;         for (int ai = 0; ai < 2; ++ai)
; #pragma unroll
;             for (int m = 0; m < 4; ++m) { bf16_t* rowp = O + (size_t)(row0 + ai * HALF + m * 16) * ldc + col0; float r[8]; const float rr = rsv[ai * 4 + m];
; #pragma unroll
;                 for (int n = 0; n < 2; ++n)
; #pragma unroll
;                     for (int j = 0; j < 4; ++j) { const float g = acc[ai][0][m][n][j] * rr, up = acc[ai][1][m][n][j] * rr;
;                         const float e = __builtin_amdgcn_exp2f(g * -1.4426950408889634f); r[n * 4 + j] = g * __builtin_amdgcn_rcpf(1.0f + e) * up; }
;                 u32x4 w; w.x = cvt_pk_bf16(r[0], r[1]); w.y = cvt_pk_bf16(r[2], r[3]); w.z = cvt_pk_bf16(r[4], r[5]); w.w = cvt_pk_bf16(r[6], r[7]);
;                 *(u32x4*)rowp = w; }
.LBB0_625:
	v_mov_b32_e32 v178, 0xbfb8aa3b
	v_mov_b32_e32 v180, 1.0
	s_waitcnt vmcnt(8)
	v_lshl_or_b32 v160, s42, 7, v147
	v_ashrrev_i32_e32 v161, 31, v160
	v_mov_b64_e32 v[154:155], s[12:13]
	v_lshlrev_b64 v[164:165], 1, v[160:161]
	v_mad_i64_i32 v[162:163], s[42:43], v142, s65, v[154:155]
	v_pk_mul_f32 v[126:127], v[158:159], v[126:127] op_sel_hi:[0,1]
	v_pk_mul_f32 v[128:129], v[158:159], v[128:129] op_sel_hi:[0,1]
	v_pk_mul_f32 v[118:119], v[158:159], v[118:119] op_sel_hi:[0,1]
	v_pk_mul_f32 v[120:121], v[158:159], v[120:121] op_sel_hi:[0,1]
	v_pk_mul_f32 v[122:123], v[158:159], v[122:123] op_sel_hi:[0,1]
	v_pk_mul_f32 v[124:125], v[158:159], v[124:125] op_sel_hi:[0,1]
	v_pk_mul_f32 v[114:115], v[158:159], v[114:115] op_sel_hi:[0,1]
	v_pk_mul_f32 v[116:117], v[158:159], v[116:117] op_sel_hi:[0,1]
	v_pk_mul_f32 v[168:169], v[178:179], v[126:127] op_sel_hi:[0,1]
	v_pk_mul_f32 v[170:171], v[178:179], v[128:129] op_sel_hi:[0,1]
	v_pk_mul_f32 v[172:173], v[178:179], v[118:119] op_sel_hi:[0,1]
	v_pk_mul_f32 v[174:175], v[178:179], v[120:121] op_sel_hi:[0,1]
	v_exp_f32_e32 v168, v168
	v_exp_f32_e32 v169, v169
	v_exp_f32_e32 v170, v170
	v_exp_f32_e32 v171, v171
	v_exp_f32_e32 v172, v172
	v_exp_f32_e32 v173, v173
	v_exp_f32_e32 v174, v174
	v_exp_f32_e32 v175, v175
	v_pk_add_f32 v[168:169], v[180:181], v[168:169] op_sel_hi:[0,1]
	v_pk_add_f32 v[170:171], v[180:181], v[170:171] op_sel_hi:[0,1]
	v_pk_add_f32 v[172:173], v[180:181], v[172:173] op_sel_hi:[0,1]
	v_pk_add_f32 v[174:175], v[180:181], v[174:175] op_sel_hi:[0,1]
	v_rcp_f32_e32 v168, v168
	v_rcp_f32_e32 v169, v169
	v_rcp_f32_e32 v170, v170
	v_rcp_f32_e32 v171, v171
	v_rcp_f32_e32 v172, v172
	v_rcp_f32_e32 v173, v173
	v_rcp_f32_e32 v174, v174
	v_rcp_f32_e32 v175, v175
	v_pk_mul_f32 v[126:127], v[126:127], v[168:169]
	v_pk_mul_f32 v[128:129], v[128:129], v[170:171]
	v_pk_mul_f32 v[118:119], v[118:119], v[172:173]
	v_pk_mul_f32 v[120:121], v[120:121], v[174:175]
	v_pk_mul_f32 v[126:127], v[126:127], v[122:123]
	v_pk_mul_f32 v[128:129], v[128:129], v[124:125]
	v_pk_mul_f32 v[118:119], v[118:119], v[114:115]
	v_pk_mul_f32 v[120:121], v[120:121], v[116:117]
	v_lshl_add_u64 v[162:163], v[162:163], 0, v[164:165]
	v_cvt_pk_bf16_f32 v122, v126, v127
	v_cvt_pk_bf16_f32 v123, v128, v129
	v_cvt_pk_bf16_f32 v124, v118, v119
	v_cvt_pk_bf16_f32 v125, v120, v121
	global_store_dwordx4 v[162:163], v[122:125], off
	v_add_u32_e32 v176, 0x10, v142
	v_mad_i64_i32 v[166:167], s[42:43], v176, s65, v[154:155]
	v_pk_mul_f32 v[110:111], v[156:157], v[110:111] op_sel_hi:[0,1]
	v_pk_mul_f32 v[112:113], v[156:157], v[112:113] op_sel_hi:[0,1]
	v_pk_mul_f32 v[102:103], v[156:157], v[102:103] op_sel_hi:[0,1]
	v_pk_mul_f32 v[104:105], v[156:157], v[104:105] op_sel_hi:[0,1]
	v_pk_mul_f32 v[106:107], v[156:157], v[106:107] op_sel_hi:[0,1]
	v_pk_mul_f32 v[108:109], v[156:157], v[108:109] op_sel_hi:[0,1]
	v_pk_mul_f32 v[98:99], v[156:157], v[98:99] op_sel_hi:[0,1]
	v_pk_mul_f32 v[100:101], v[156:157], v[100:101] op_sel_hi:[0,1]
	v_pk_mul_f32 v[168:169], v[178:179], v[110:111] op_sel_hi:[0,1]
	v_pk_mul_f32 v[170:171], v[178:179], v[112:113] op_sel_hi:[0,1]
	v_pk_mul_f32 v[172:173], v[178:179], v[102:103] op_sel_hi:[0,1]
	v_pk_mul_f32 v[174:175], v[178:179], v[104:105] op_sel_hi:[0,1]
	v_exp_f32_e32 v168, v168
	v_exp_f32_e32 v169, v169
	v_exp_f32_e32 v170, v170
	v_exp_f32_e32 v171, v171
	v_exp_f32_e32 v172, v172
	v_exp_f32_e32 v173, v173
	v_exp_f32_e32 v174, v174
	v_exp_f32_e32 v175, v175
	v_pk_add_f32 v[168:169], v[180:181], v[168:169] op_sel_hi:[0,1]
	v_pk_add_f32 v[170:171], v[180:181], v[170:171] op_sel_hi:[0,1]
	v_pk_add_f32 v[172:173], v[180:181], v[172:173] op_sel_hi:[0,1]
	v_pk_add_f32 v[174:175], v[180:181], v[174:175] op_sel_hi:[0,1]
	v_rcp_f32_e32 v168, v168
	v_rcp_f32_e32 v169, v169
	v_rcp_f32_e32 v170, v170
	v_rcp_f32_e32 v171, v171
	v_rcp_f32_e32 v172, v172
	v_rcp_f32_e32 v173, v173
	v_rcp_f32_e32 v174, v174
	v_rcp_f32_e32 v175, v175
	v_pk_mul_f32 v[110:111], v[110:111], v[168:169]
	v_pk_mul_f32 v[112:113], v[112:113], v[170:171]
	v_pk_mul_f32 v[102:103], v[102:103], v[172:173]
	v_pk_mul_f32 v[104:105], v[104:105], v[174:175]
	v_pk_mul_f32 v[110:111], v[110:111], v[106:107]
	v_pk_mul_f32 v[112:113], v[112:113], v[108:109]
	v_pk_mul_f32 v[102:103], v[102:103], v[98:99]
	v_pk_mul_f32 v[104:105], v[104:105], v[100:101]
	v_lshl_add_u64 v[166:167], v[166:167], 0, v[164:165]
	v_cvt_pk_bf16_f32 v106, v110, v111
	v_cvt_pk_bf16_f32 v107, v112, v113
	v_cvt_pk_bf16_f32 v108, v102, v103
	v_cvt_pk_bf16_f32 v109, v104, v105
	global_store_dwordx4 v[166:167], v[106:109], off
	v_add_u32_e32 v176, 0x20, v142
	v_mad_i64_i32 v[162:163], s[42:43], v176, s65, v[154:155]
	v_pk_mul_f32 v[94:95], v[152:153], v[94:95] op_sel_hi:[0,1]
	v_pk_mul_f32 v[96:97], v[152:153], v[96:97] op_sel_hi:[0,1]
	v_pk_mul_f32 v[86:87], v[152:153], v[86:87] op_sel_hi:[0,1]
	v_pk_mul_f32 v[88:89], v[152:153], v[88:89] op_sel_hi:[0,1]
	v_pk_mul_f32 v[90:91], v[152:153], v[90:91] op_sel_hi:[0,1]
	v_pk_mul_f32 v[92:93], v[152:153], v[92:93] op_sel_hi:[0,1]
	v_pk_mul_f32 v[82:83], v[152:153], v[82:83] op_sel_hi:[0,1]
	v_pk_mul_f32 v[84:85], v[152:153], v[84:85] op_sel_hi:[0,1]
	v_pk_mul_f32 v[168:169], v[178:179], v[94:95] op_sel_hi:[0,1]
	v_pk_mul_f32 v[170:171], v[178:179], v[96:97] op_sel_hi:[0,1]
	v_pk_mul_f32 v[172:173], v[178:179], v[86:87] op_sel_hi:[0,1]
	v_pk_mul_f32 v[174:175], v[178:179], v[88:89] op_sel_hi:[0,1]
	v_exp_f32_e32 v168, v168
	v_exp_f32_e32 v169, v169
	v_exp_f32_e32 v170, v170
	v_exp_f32_e32 v171, v171
	v_exp_f32_e32 v172, v172
	v_exp_f32_e32 v173, v173
	v_exp_f32_e32 v174, v174
	v_exp_f32_e32 v175, v175
; __device__ __forceinline__ unsigned cvt_pk_bf16(float lo, float hi) { unsigned r; asm volatile("v_cvt_pk_bf16_f32 %0, %1, %2" : "=v"(r) : "v"(lo), "v"(hi)); return r; }
;     __device__ __forceinline__ void operator()(const f32x4 (&acc)[2][2][4][2], const Unit& u, int wr, int wc, int fr, int fq, const float (&rsv)[8]) const {
;         const int row0 = u.pm * BM + wr * 64 + fr, col0 = u.pn * HALF + wc * 32 + 8 * fq;
; #pragma unroll
;         for (int ai = 0; ai < 2; ++ai)
; #pragma unroll
;             for (int m = 0; m < 4; ++m) { bf16_t* rowp = O + (size_t)(row0 + ai * HALF + m * 16) * ldc + col0; float r[8]; const float rr = rsv[ai * 4 + m];
; #pragma unroll
;                 for (int n = 0; n < 2; ++n)
; #pragma unroll
;                     for (int j = 0; j < 4; ++j) { const float g = acc[ai][0][m][n][j] * rr, up = acc[ai][1][m][n][j] * rr;
;                         const float e = __builtin_amdgcn_exp2f(g * -1.4426950408889634f); r[n * 4 + j] = g * __builtin_amdgcn_rcpf(1.0f + e) * up; }
;                 u32x4 w; w.x = cvt_pk_bf16(r[0], r[1]); w.y = cvt_pk_bf16(r[2], r[3]); w.z = cvt_pk_bf16(r[4], r[5]); w.w = cvt_pk_bf16(r[6], r[7]);
;                 *(u32x4*)rowp = w; }
	v_pk_add_f32 v[168:169], v[180:181], v[168:169] op_sel_hi:[0,1]
	v_pk_add_f32 v[170:171], v[180:181], v[170:171] op_sel_hi:[0,1]
	v_pk_add_f32 v[172:173], v[180:181], v[172:173] op_sel_hi:[0,1]
	v_pk_add_f32 v[174:175], v[180:181], v[174:175] op_sel_hi:[0,1]
	v_rcp_f32_e32 v168, v168
	v_rcp_f32_e32 v169, v169
	v_rcp_f32_e32 v170, v170
	v_rcp_f32_e32 v171, v171
	v_rcp_f32_e32 v172, v172
	v_rcp_f32_e32 v173, v173
	v_rcp_f32_e32 v174, v174
	v_rcp_f32_e32 v175, v175
	v_pk_mul_f32 v[94:95], v[94:95], v[168:169]
	v_pk_mul_f32 v[96:97], v[96:97], v[170:171]
	v_pk_mul_f32 v[86:87], v[86:87], v[172:173]
	v_pk_mul_f32 v[88:89], v[88:89], v[174:175]
	v_pk_mul_f32 v[94:95], v[94:95], v[90:91]
	v_pk_mul_f32 v[96:97], v[96:97], v[92:93]
	v_pk_mul_f32 v[86:87], v[86:87], v[82:83]
	v_pk_mul_f32 v[88:89], v[88:89], v[84:85]
	v_lshl_add_u64 v[162:163], v[162:163], 0, v[164:165]
	v_cvt_pk_bf16_f32 v90, v94, v95
	v_cvt_pk_bf16_f32 v91, v96, v97
	v_cvt_pk_bf16_f32 v92, v86, v87
	v_cvt_pk_bf16_f32 v93, v88, v89
	global_store_dwordx4 v[162:163], v[90:93], off
	v_add_u32_e32 v176, 0x30, v142
	v_mad_i64_i32 v[166:167], s[42:43], v176, s65, v[154:155]
	v_pk_mul_f32 v[78:79], v[150:151], v[78:79] op_sel_hi:[0,1]
	v_pk_mul_f32 v[80:81], v[150:151], v[80:81] op_sel_hi:[0,1]
	v_pk_mul_f32 v[70:71], v[150:151], v[70:71] op_sel_hi:[0,1]
	v_pk_mul_f32 v[72:73], v[150:151], v[72:73] op_sel_hi:[0,1]
	v_pk_mul_f32 v[74:75], v[150:151], v[74:75] op_sel_hi:[0,1]
	v_pk_mul_f32 v[76:77], v[150:151], v[76:77] op_sel_hi:[0,1]
	v_pk_mul_f32 v[66:67], v[150:151], v[66:67] op_sel_hi:[0,1]
	v_pk_mul_f32 v[68:69], v[150:151], v[68:69] op_sel_hi:[0,1]
	v_pk_mul_f32 v[168:169], v[178:179], v[78:79] op_sel_hi:[0,1]
	v_pk_mul_f32 v[170:171], v[178:179], v[80:81] op_sel_hi:[0,1]
	v_pk_mul_f32 v[172:173], v[178:179], v[70:71] op_sel_hi:[0,1]
	v_pk_mul_f32 v[174:175], v[178:179], v[72:73] op_sel_hi:[0,1]
	v_exp_f32_e32 v168, v168
	v_exp_f32_e32 v169, v169
	v_exp_f32_e32 v170, v170
	v_exp_f32_e32 v171, v171
	v_exp_f32_e32 v172, v172
	v_exp_f32_e32 v173, v173
	v_exp_f32_e32 v174, v174
	v_exp_f32_e32 v175, v175
	v_pk_add_f32 v[168:169], v[180:181], v[168:169] op_sel_hi:[0,1]
	v_pk_add_f32 v[170:171], v[180:181], v[170:171] op_sel_hi:[0,1]
	v_pk_add_f32 v[172:173], v[180:181], v[172:173] op_sel_hi:[0,1]
	v_pk_add_f32 v[174:175], v[180:181], v[174:175] op_sel_hi:[0,1]
	v_rcp_f32_e32 v168, v168
	v_rcp_f32_e32 v169, v169
	v_rcp_f32_e32 v170, v170
	v_rcp_f32_e32 v171, v171
	v_rcp_f32_e32 v172, v172
	v_rcp_f32_e32 v173, v173
	v_rcp_f32_e32 v174, v174
	v_rcp_f32_e32 v175, v175
	v_pk_mul_f32 v[78:79], v[78:79], v[168:169]
	v_pk_mul_f32 v[80:81], v[80:81], v[170:171]
	v_pk_mul_f32 v[70:71], v[70:71], v[172:173]
	v_pk_mul_f32 v[72:73], v[72:73], v[174:175]
	v_pk_mul_f32 v[78:79], v[78:79], v[74:75]
	v_pk_mul_f32 v[80:81], v[80:81], v[76:77]
	v_pk_mul_f32 v[70:71], v[70:71], v[66:67]
	v_pk_mul_f32 v[72:73], v[72:73], v[68:69]
	v_lshl_add_u64 v[166:167], v[166:167], 0, v[164:165]
	v_cvt_pk_bf16_f32 v74, v78, v79
	v_cvt_pk_bf16_f32 v75, v80, v81
	v_cvt_pk_bf16_f32 v76, v70, v71
	v_cvt_pk_bf16_f32 v77, v72, v73
	global_store_dwordx4 v[166:167], v[74:77], off
	v_add_u32_e32 v176, 0x80, v142
	v_mad_i64_i32 v[162:163], s[42:43], v176, s65, v[154:155]
	v_pk_mul_f32 v[62:63], v[148:149], v[62:63] op_sel_hi:[0,1]
	v_pk_mul_f32 v[64:65], v[148:149], v[64:65] op_sel_hi:[0,1]
	v_pk_mul_f32 v[54:55], v[148:149], v[54:55] op_sel_hi:[0,1]
	v_pk_mul_f32 v[56:57], v[148:149], v[56:57] op_sel_hi:[0,1]
	v_pk_mul_f32 v[58:59], v[148:149], v[58:59] op_sel_hi:[0,1]
	v_pk_mul_f32 v[60:61], v[148:149], v[60:61] op_sel_hi:[0,1]
	v_pk_mul_f32 v[50:51], v[148:149], v[50:51] op_sel_hi:[0,1]
	v_pk_mul_f32 v[52:53], v[148:149], v[52:53] op_sel_hi:[0,1]
	v_pk_mul_f32 v[168:169], v[178:179], v[62:63] op_sel_hi:[0,1]
	v_pk_mul_f32 v[170:171], v[178:179], v[64:65] op_sel_hi:[0,1]
	v_pk_mul_f32 v[172:173], v[178:179], v[54:55] op_sel_hi:[0,1]
	v_pk_mul_f32 v[174:175], v[178:179], v[56:57] op_sel_hi:[0,1]
	v_exp_f32_e32 v168, v168
	v_exp_f32_e32 v169, v169
	v_exp_f32_e32 v170, v170
	v_exp_f32_e32 v171, v171
	v_exp_f32_e32 v172, v172
	v_exp_f32_e32 v173, v173
	v_exp_f32_e32 v174, v174
	v_exp_f32_e32 v175, v175
	v_pk_add_f32 v[168:169], v[180:181], v[168:169] op_sel_hi:[0,1]
	v_pk_add_f32 v[170:171], v[180:181], v[170:171] op_sel_hi:[0,1]
	v_pk_add_f32 v[172:173], v[180:181], v[172:173] op_sel_hi:[0,1]
	v_pk_add_f32 v[174:175], v[180:181], v[174:175] op_sel_hi:[0,1]
	v_rcp_f32_e32 v168, v168
	v_rcp_f32_e32 v169, v169
	v_rcp_f32_e32 v170, v170
	v_rcp_f32_e32 v171, v171
	v_rcp_f32_e32 v172, v172
	v_rcp_f32_e32 v173, v173
	v_rcp_f32_e32 v174, v174
	v_rcp_f32_e32 v175, v175
	v_pk_mul_f32 v[62:63], v[62:63], v[168:169]
	v_pk_mul_f32 v[64:65], v[64:65], v[170:171]
	v_pk_mul_f32 v[54:55], v[54:55], v[172:173]
	v_pk_mul_f32 v[56:57], v[56:57], v[174:175]
	v_pk_mul_f32 v[62:63], v[62:63], v[58:59]
	v_pk_mul_f32 v[64:65], v[64:65], v[60:61]
	v_pk_mul_f32 v[54:55], v[54:55], v[50:51]
	v_pk_mul_f32 v[56:57], v[56:57], v[52:53]
	v_lshl_add_u64 v[162:163], v[162:163], 0, v[164:165]
	v_cvt_pk_bf16_f32 v58, v62, v63
	v_cvt_pk_bf16_f32 v59, v64, v65
	v_cvt_pk_bf16_f32 v60, v54, v55
	v_cvt_pk_bf16_f32 v61, v56, v57
	global_store_dwordx4 v[162:163], v[58:61], off
	v_add_u32_e32 v176, 0x90, v142
	v_mad_i64_i32 v[166:167], s[42:43], v176, s65, v[154:155]
	v_pk_mul_f32 v[46:47], v[146:147], v[46:47] op_sel_hi:[0,1]
	v_pk_mul_f32 v[48:49], v[146:147], v[48:49] op_sel_hi:[0,1]
	v_pk_mul_f32 v[38:39], v[146:147], v[38:39] op_sel_hi:[0,1]
	v_pk_mul_f32 v[40:41], v[146:147], v[40:41] op_sel_hi:[0,1]
	v_pk_mul_f32 v[42:43], v[146:147], v[42:43] op_sel_hi:[0,1]
; __device__ __forceinline__ unsigned cvt_pk_bf16(float lo, float hi) { unsigned r; asm volatile("v_cvt_pk_bf16_f32 %0, %1, %2" : "=v"(r) : "v"(lo), "v"(hi)); return r; }
; #define PG8_BAR __builtin_amdgcn_s_barrier()
;     __device__ __forceinline__ void operator()(const f32x4 (&acc)[2][2][4][2], const Unit& u, int wr, int wc, int fr, int fq, const float (&rsv)[8]) const {
;         const int row0 = u.pm * BM + wr * 64 + fr, col0 = u.pn * HALF + wc * 32 + 8 * fq;
; #pragma unroll
;         for (int ai = 0; ai < 2; ++ai)
; #pragma unroll
;             for (int m = 0; m < 4; ++m) { bf16_t* rowp = O + (size_t)(row0 + ai * HALF + m * 16) * ldc + col0; float r[8]; const float rr = rsv[ai * 4 + m];
; #pragma unroll
;                 for (int n = 0; n < 2; ++n)
; #pragma unroll
;                     for (int j = 0; j < 4; ++j) { const float g = acc[ai][0][m][n][j] * rr, up = acc[ai][1][m][n][j] * rr;
;                         const float e = __builtin_amdgcn_exp2f(g * -1.4426950408889634f); r[n * 4 + j] = g * __builtin_amdgcn_rcpf(1.0f + e) * up; }
;                 u32x4 w; w.x = cvt_pk_bf16(r[0], r[1]); w.y = cvt_pk_bf16(r[2], r[3]); w.z = cvt_pk_bf16(r[4], r[5]); w.w = cvt_pk_bf16(r[6], r[7]);
;                 *(u32x4*)rowp = w; }
; template <class Epi, class Sched, bool ALIGN_EPI = false, bool SP2 = false>
; __device__ __forceinline__ void gemm_phase(PG8_LAS unsigned char* lds, const Gemm g, const Sched& S, const Epi& E, const int tid_in) {
;     ...
;         if constexpr (!Epi::AFTER_DRAIN) { E(acc, cur, wr, wc, fr, fq, rsv); S.done(cur); }
;         if (!has_next) break;
; #pragma unroll
;         for (int a = 0; a < 2; ++a)
; #pragma unroll
;             for (int b = 0; b < 2; ++b)
; #pragma unroll
;                 for (int m = 0; m < 4; ++m)
; #pragma unroll
;                     for (int n = 0; n < 2; ++n) acc[a][b][m][n] = (f32x4){0.f, 0.f, 0.f, 0.f};
;         cur = nxt; cA = nA; cB = nB; ++ui;
;         if constexpr (ALIGN_EPI) { if (wr == 1) PG8_BAR; }
;     }
	v_pk_mul_f32 v[44:45], v[146:147], v[44:45] op_sel_hi:[0,1]
	v_pk_mul_f32 v[34:35], v[146:147], v[34:35] op_sel_hi:[0,1]
	v_pk_mul_f32 v[36:37], v[146:147], v[36:37] op_sel_hi:[0,1]
	v_pk_mul_f32 v[168:169], v[178:179], v[46:47] op_sel_hi:[0,1]
	v_pk_mul_f32 v[170:171], v[178:179], v[48:49] op_sel_hi:[0,1]
	v_pk_mul_f32 v[172:173], v[178:179], v[38:39] op_sel_hi:[0,1]
	v_pk_mul_f32 v[174:175], v[178:179], v[40:41] op_sel_hi:[0,1]
	v_exp_f32_e32 v168, v168
	v_exp_f32_e32 v169, v169
	v_exp_f32_e32 v170, v170
	v_exp_f32_e32 v171, v171
	v_exp_f32_e32 v172, v172
	v_exp_f32_e32 v173, v173
	v_exp_f32_e32 v174, v174
	v_exp_f32_e32 v175, v175
	v_pk_add_f32 v[168:169], v[180:181], v[168:169] op_sel_hi:[0,1]
	v_pk_add_f32 v[170:171], v[180:181], v[170:171] op_sel_hi:[0,1]
	v_pk_add_f32 v[172:173], v[180:181], v[172:173] op_sel_hi:[0,1]
	v_pk_add_f32 v[174:175], v[180:181], v[174:175] op_sel_hi:[0,1]
	v_rcp_f32_e32 v168, v168
	v_rcp_f32_e32 v169, v169
	v_rcp_f32_e32 v170, v170
	v_rcp_f32_e32 v171, v171
	v_rcp_f32_e32 v172, v172
	v_rcp_f32_e32 v173, v173
	v_rcp_f32_e32 v174, v174
	v_rcp_f32_e32 v175, v175
	v_pk_mul_f32 v[46:47], v[46:47], v[168:169]
	v_pk_mul_f32 v[48:49], v[48:49], v[170:171]
	v_pk_mul_f32 v[38:39], v[38:39], v[172:173]
	v_pk_mul_f32 v[40:41], v[40:41], v[174:175]
	v_pk_mul_f32 v[46:47], v[46:47], v[42:43]
	v_pk_mul_f32 v[48:49], v[48:49], v[44:45]
	v_pk_mul_f32 v[38:39], v[38:39], v[34:35]
	v_pk_mul_f32 v[40:41], v[40:41], v[36:37]
	v_lshl_add_u64 v[166:167], v[166:167], 0, v[164:165]
	v_cvt_pk_bf16_f32 v42, v46, v47
	v_cvt_pk_bf16_f32 v43, v48, v49
	v_cvt_pk_bf16_f32 v44, v38, v39
	v_cvt_pk_bf16_f32 v45, v40, v41
	global_store_dwordx4 v[166:167], v[42:45], off
	v_add_u32_e32 v176, 0xa0, v142
	v_mad_i64_i32 v[162:163], s[42:43], v176, s65, v[154:155]
	v_pk_mul_f32 v[30:31], v[144:145], v[30:31] op_sel_hi:[0,1]
	v_pk_mul_f32 v[32:33], v[144:145], v[32:33] op_sel_hi:[0,1]
	v_pk_mul_f32 v[22:23], v[144:145], v[22:23] op_sel_hi:[0,1]
	v_pk_mul_f32 v[24:25], v[144:145], v[24:25] op_sel_hi:[0,1]
	v_pk_mul_f32 v[26:27], v[144:145], v[26:27] op_sel_hi:[0,1]
	v_pk_mul_f32 v[28:29], v[144:145], v[28:29] op_sel_hi:[0,1]
	v_pk_mul_f32 v[18:19], v[144:145], v[18:19] op_sel_hi:[0,1]
	v_pk_mul_f32 v[20:21], v[144:145], v[20:21] op_sel_hi:[0,1]
	v_pk_mul_f32 v[168:169], v[178:179], v[30:31] op_sel_hi:[0,1]
	v_pk_mul_f32 v[170:171], v[178:179], v[32:33] op_sel_hi:[0,1]
	v_pk_mul_f32 v[172:173], v[178:179], v[22:23] op_sel_hi:[0,1]
	v_pk_mul_f32 v[174:175], v[178:179], v[24:25] op_sel_hi:[0,1]
	v_exp_f32_e32 v168, v168
	v_exp_f32_e32 v169, v169
	v_exp_f32_e32 v170, v170
	v_exp_f32_e32 v171, v171
	v_exp_f32_e32 v172, v172
	v_exp_f32_e32 v173, v173
	v_exp_f32_e32 v174, v174
	v_exp_f32_e32 v175, v175
	v_pk_add_f32 v[168:169], v[180:181], v[168:169] op_sel_hi:[0,1]
	v_pk_add_f32 v[170:171], v[180:181], v[170:171] op_sel_hi:[0,1]
	v_pk_add_f32 v[172:173], v[180:181], v[172:173] op_sel_hi:[0,1]
	v_pk_add_f32 v[174:175], v[180:181], v[174:175] op_sel_hi:[0,1]
	v_rcp_f32_e32 v168, v168
	v_rcp_f32_e32 v169, v169
	v_rcp_f32_e32 v170, v170
	v_rcp_f32_e32 v171, v171
	v_rcp_f32_e32 v172, v172
	v_rcp_f32_e32 v173, v173
	v_rcp_f32_e32 v174, v174
	v_rcp_f32_e32 v175, v175
	v_pk_mul_f32 v[30:31], v[30:31], v[168:169]
	v_pk_mul_f32 v[32:33], v[32:33], v[170:171]
	v_pk_mul_f32 v[22:23], v[22:23], v[172:173]
	v_pk_mul_f32 v[24:25], v[24:25], v[174:175]
	v_pk_mul_f32 v[30:31], v[30:31], v[26:27]
	v_pk_mul_f32 v[32:33], v[32:33], v[28:29]
	v_pk_mul_f32 v[22:23], v[22:23], v[18:19]
	v_pk_mul_f32 v[24:25], v[24:25], v[20:21]
	v_lshl_add_u64 v[162:163], v[162:163], 0, v[164:165]
	v_cvt_pk_bf16_f32 v26, v30, v31
	v_cvt_pk_bf16_f32 v27, v32, v33
	v_cvt_pk_bf16_f32 v28, v22, v23
	v_cvt_pk_bf16_f32 v29, v24, v25
	global_store_dwordx4 v[162:163], v[26:29], off
	v_add_u32_e32 v176, 0xb0, v142
	v_mad_i64_i32 v[166:167], s[42:43], v176, s65, v[154:155]
	v_pk_mul_f32 v[14:15], v[140:141], v[14:15] op_sel_hi:[0,1]
	v_pk_mul_f32 v[16:17], v[140:141], v[16:17] op_sel_hi:[0,1]
	v_pk_mul_f32 v[6:7], v[140:141], v[6:7] op_sel_hi:[0,1]
	v_pk_mul_f32 v[8:9], v[140:141], v[8:9] op_sel_hi:[0,1]
	v_pk_mul_f32 v[10:11], v[140:141], v[10:11] op_sel_hi:[0,1]
	v_pk_mul_f32 v[12:13], v[140:141], v[12:13] op_sel_hi:[0,1]
	v_pk_mul_f32 v[2:3], v[140:141], v[2:3] op_sel_hi:[0,1]
	v_pk_mul_f32 v[4:5], v[140:141], v[4:5] op_sel_hi:[0,1]
	v_pk_mul_f32 v[168:169], v[178:179], v[14:15] op_sel_hi:[0,1]
	v_pk_mul_f32 v[170:171], v[178:179], v[16:17] op_sel_hi:[0,1]
	v_pk_mul_f32 v[172:173], v[178:179], v[6:7] op_sel_hi:[0,1]
	v_pk_mul_f32 v[174:175], v[178:179], v[8:9] op_sel_hi:[0,1]
	v_exp_f32_e32 v168, v168
	v_exp_f32_e32 v169, v169
	v_exp_f32_e32 v170, v170
	v_exp_f32_e32 v171, v171
	v_exp_f32_e32 v172, v172
	v_exp_f32_e32 v173, v173
	v_exp_f32_e32 v174, v174
	v_exp_f32_e32 v175, v175
	v_pk_add_f32 v[168:169], v[180:181], v[168:169] op_sel_hi:[0,1]
	v_pk_add_f32 v[170:171], v[180:181], v[170:171] op_sel_hi:[0,1]
	v_pk_add_f32 v[172:173], v[180:181], v[172:173] op_sel_hi:[0,1]
	v_pk_add_f32 v[174:175], v[180:181], v[174:175] op_sel_hi:[0,1]
	v_rcp_f32_e32 v168, v168
	v_rcp_f32_e32 v169, v169
	v_rcp_f32_e32 v170, v170
	v_rcp_f32_e32 v171, v171
	v_rcp_f32_e32 v172, v172
	v_rcp_f32_e32 v173, v173
	v_rcp_f32_e32 v174, v174
	v_rcp_f32_e32 v175, v175
	v_pk_mul_f32 v[14:15], v[14:15], v[168:169]
	v_pk_mul_f32 v[16:17], v[16:17], v[170:171]
	v_pk_mul_f32 v[6:7], v[6:7], v[172:173]
	v_pk_mul_f32 v[8:9], v[8:9], v[174:175]
	v_pk_mul_f32 v[14:15], v[14:15], v[10:11]
	v_pk_mul_f32 v[16:17], v[16:17], v[12:13]
	v_pk_mul_f32 v[6:7], v[6:7], v[2:3]
	v_pk_mul_f32 v[8:9], v[8:9], v[4:5]
	v_lshl_add_u64 v[166:167], v[166:167], 0, v[164:165]
	v_cvt_pk_bf16_f32 v10, v14, v15
	v_cvt_pk_bf16_f32 v11, v16, v17
	v_cvt_pk_bf16_f32 v12, v6, v7
	v_cvt_pk_bf16_f32 v13, v8, v9
	global_store_dwordx4 v[166:167], v[10:13], off
	s_mov_b64 s[70:71], -1
	s_andn2_b64 vcc, exec, s[4:5]
	s_cbranch_vccnz .LBB0_618
	s_andn2_b64 vcc, exec, s[10:11]
	s_cbranch_vccnz .LBB0_617
	s_barrier
	s_branch .LBB0_617
